# attention tile step restructured: K/V fragment LDS reads pipelined 3-5 deep with counted waits, in-place exp2, permlane32 swap for lane-half exchange, sel-mask fast path
# speedup vs baseline: 1.0130x; 1.0122x over previous
.LBB0_961:
	v_lshrrev_b32_e32 v0, s28, v78
	v_and_b32_e32 v0, 1, v0
	v_cmp_eq_u32_e64 s[0:1], 1, v0
	v_bfe_u32 v0, v78, s28, 1
	v_cmp_ne_u32_e32 vcc, 0, v0
	s_cbranch_vccz .LBB0_967
	ds_read_b128 v[38:41], v242
	ds_read_b128 v[34:37], v242 offset:4608
	ds_read_b128 v[102:105], v242 offset:32
	ds_read_b128 v[106:109], v242 offset:4640
	ds_read_b128 v[250:253], v242 offset:64
	s_cmp_lg_u64 vcc, -1
	s_cselect_b64 s[80:81], -1, 0
	s_cmp_eq_u32 s28, s22
	s_cselect_b64 vcc, -1, 0
	s_or_b64 s[80:81], s[80:81], vcc
	s_andn2_b64 vcc, exec, s[80:81]
	s_waitcnt lgkmcnt(4)
	v_mfma_f32_32x32x16_bf16 v[50:65], v[38:41], v[80:83], 0
	s_waitcnt lgkmcnt(3)
	v_mfma_f32_32x32x16_bf16 v[34:49], v[34:37], v[80:83], 0
	s_waitcnt lgkmcnt(2)
	v_mfma_f32_32x32x16_bf16 v[50:65], v[102:105], v[84:87], v[50:65]
	ds_read_b128 v[102:105], v242 offset:4672
	s_waitcnt lgkmcnt(2)
	v_mfma_f32_32x32x16_bf16 v[34:49], v[106:109], v[84:87], v[34:49]
	ds_read_b128 v[106:109], v242 offset:96
	s_waitcnt lgkmcnt(2)
	v_mfma_f32_32x32x16_bf16 v[50:65], v[250:253], v[88:91], v[50:65]
	ds_read_b128 v[250:253], v242 offset:4704
	s_waitcnt lgkmcnt(2)
	v_mfma_f32_32x32x16_bf16 v[34:49], v[102:105], v[88:91], v[34:49]
	s_waitcnt lgkmcnt(1)
	v_mfma_f32_32x32x16_bf16 v[50:65], v[106:109], v[92:95], v[50:65]
	s_waitcnt lgkmcnt(0)
	v_mfma_f32_32x32x16_bf16 v[34:49], v[250:253], v[92:95], v[34:49]
	ds_read_b64_tr_b16 v[250:251], v199 offset:9216
	ds_read_b64_tr_b16 v[252:253], v199 offset:10752
	ds_read_b64_tr_b16 v[104:105], v199 offset:9280
	ds_read_b64_tr_b16 v[106:107], v199 offset:10816
	ds_read_b64_tr_b16 v[108:109], v199 offset:15360
	ds_read_b64_tr_b16 v[110:111], v199 offset:16896
	s_cbranch_vccnz .Latt_nm_0
	s_cmp_eq_u32 s28, s22
	s_cbranch_scc1 .Latt_sl_0
	s_mov_b64 s[80:81], s[0:1]
	s_branch .LBB0_964
.Latt_sl_0:
	s_lshl_b32 s2, s28, 6
	v_subrev_u32_e32 v0, s2, v243
	v_subrev_u32_e32 v101, 32, v0
	v_cmp_le_i32_e32 vcc, v118, v0
	v_cmp_le_i32_e64 s[80:81], v118, v101
	s_and_b64 vcc, s[0:1], vcc
	s_nop 2
	v_cndmask_b32_e32 v50, v236, v50, vcc
	s_and_b64 vcc, s[0:1], s[80:81]
	v_cndmask_b32_e32 v34, v236, v34, vcc
	v_cmp_lt_i32_e32 vcc, v118, v0
	v_cmp_lt_i32_e64 s[80:81], v118, v101
	s_and_b64 vcc, s[0:1], vcc
	v_cndmask_b32_e32 v51, v236, v51, vcc
	s_and_b64 vcc, s[0:1], s[80:81]
	v_cndmask_b32_e32 v35, v236, v35, vcc
	v_cmp_le_i32_e32 vcc, v137, v0
	v_cmp_le_i32_e64 s[80:81], v137, v101
	s_and_b64 vcc, s[0:1], vcc
	v_cndmask_b32_e32 v52, v236, v52, vcc
	s_and_b64 vcc, s[0:1], s[80:81]
	v_cndmask_b32_e32 v36, v236, v36, vcc
	v_cmp_le_i32_e32 vcc, v138, v0
	v_cmp_le_i32_e64 s[80:81], v138, v101
	s_and_b64 vcc, s[0:1], vcc
	v_cndmask_b32_e32 v53, v236, v53, vcc
	s_and_b64 vcc, s[0:1], s[80:81]
	v_cndmask_b32_e32 v37, v236, v37, vcc
	v_cmp_le_i32_e32 vcc, v139, v0
	v_cmp_le_i32_e64 s[80:81], v139, v101
	s_and_b64 vcc, s[0:1], vcc
	v_cndmask_b32_e32 v54, v236, v54, vcc
	s_and_b64 vcc, s[0:1], s[80:81]
	v_cndmask_b32_e32 v38, v236, v38, vcc
	v_cmp_le_i32_e32 vcc, v140, v0
	v_cmp_le_i32_e64 s[80:81], v140, v101
	s_and_b64 vcc, s[0:1], vcc
	v_cndmask_b32_e32 v55, v236, v55, vcc
	s_and_b64 vcc, s[0:1], s[80:81]
	v_cndmask_b32_e32 v39, v236, v39, vcc
	v_cmp_le_i32_e32 vcc, v141, v0
	v_cmp_le_i32_e64 s[80:81], v141, v101
	s_and_b64 vcc, s[0:1], vcc
	v_cndmask_b32_e32 v56, v236, v56, vcc
	s_and_b64 vcc, s[0:1], s[80:81]
	v_cndmask_b32_e32 v40, v236, v40, vcc
	v_cmp_le_i32_e32 vcc, v142, v0
	v_cmp_le_i32_e64 s[80:81], v142, v101
	s_and_b64 vcc, s[0:1], vcc
	v_cndmask_b32_e32 v57, v236, v57, vcc
	s_and_b64 vcc, s[0:1], s[80:81]
	v_cndmask_b32_e32 v41, v236, v41, vcc
	v_cmp_le_i32_e32 vcc, v143, v0
	v_cmp_le_i32_e64 s[80:81], v143, v101
	s_and_b64 vcc, s[0:1], vcc
	v_cndmask_b32_e32 v58, v236, v58, vcc
	s_and_b64 vcc, s[0:1], s[80:81]
	v_cndmask_b32_e32 v42, v236, v42, vcc
	v_cmp_le_i32_e32 vcc, v144, v0
	v_cmp_le_i32_e64 s[80:81], v144, v101
	s_and_b64 vcc, s[0:1], vcc
	v_cndmask_b32_e32 v59, v236, v59, vcc
	s_and_b64 vcc, s[0:1], s[80:81]
	v_cndmask_b32_e32 v43, v236, v43, vcc
	v_cmp_le_i32_e32 vcc, v145, v0
	v_cmp_le_i32_e64 s[80:81], v145, v101
	s_and_b64 vcc, s[0:1], vcc
	v_cndmask_b32_e32 v60, v236, v60, vcc
	s_and_b64 vcc, s[0:1], s[80:81]
	v_cndmask_b32_e32 v44, v236, v44, vcc
	v_cmp_le_i32_e32 vcc, v146, v0
	v_cmp_le_i32_e64 s[80:81], v146, v101
	s_and_b64 vcc, s[0:1], vcc
	v_cndmask_b32_e32 v61, v236, v61, vcc
	s_and_b64 vcc, s[0:1], s[80:81]
	v_cndmask_b32_e32 v45, v236, v45, vcc
	v_cmp_le_i32_e32 vcc, v147, v0
	v_cmp_le_i32_e64 s[80:81], v147, v101
	s_and_b64 vcc, s[0:1], vcc
	v_cndmask_b32_e32 v62, v236, v62, vcc
	s_and_b64 vcc, s[0:1], s[80:81]
	v_cndmask_b32_e32 v46, v236, v46, vcc
	v_cmp_le_i32_e32 vcc, v148, v0
	v_cmp_le_i32_e64 s[80:81], v148, v101
	s_and_b64 vcc, s[0:1], vcc
	v_cndmask_b32_e32 v63, v236, v63, vcc
	s_and_b64 vcc, s[0:1], s[80:81]
	v_cndmask_b32_e32 v47, v236, v47, vcc
	v_cmp_le_i32_e32 vcc, v149, v0
	v_cmp_le_i32_e64 s[80:81], v149, v101
	s_and_b64 vcc, s[0:1], vcc
	v_cndmask_b32_e32 v64, v236, v64, vcc
	s_and_b64 vcc, s[0:1], s[80:81]
	v_cndmask_b32_e32 v48, v236, v48, vcc
	v_cmp_le_i32_e32 vcc, v150, v0
	v_cmp_le_i32_e64 s[80:81], v150, v101
	s_and_b64 vcc, s[0:1], vcc
	v_cndmask_b32_e32 v65, v236, v65, vcc
	s_and_b64 vcc, s[0:1], s[80:81]
	v_cndmask_b32_e32 v49, v236, v49, vcc
	s_mov_b64 s[80:81], -1
	s_branch .LBB0_964
.Latt_nm_0:
	s_mov_b64 s[80:81], -1
.LBB0_964:
	s_nop 10
	v_max3_f32 v0, v50, v34, v51
	v_max3_f32 v101, v35, v52, v36
	v_max3_f32 v102, v53, v37, v54
	v_max3_f32 v103, v38, v55, v39
	v_max3_f32 v0, v0, v56, v40
	v_max3_f32 v101, v101, v57, v41
	v_max3_f32 v102, v102, v58, v42
	v_max3_f32 v103, v103, v59, v43
	v_max3_f32 v0, v0, v60, v44
	v_max3_f32 v101, v101, v61, v45
	v_max3_f32 v102, v102, v62, v46
	v_max3_f32 v103, v103, v63, v47
	v_max3_f32 v0, v0, v64, v48
	v_max3_f32 v101, v101, v65, v49
	v_max3_f32 v0, v0, v102, v103
	v_max_f32_e32 v0, v0, v101
	v_mov_b32_e32 v101, v0
	s_nop 1
	v_permlane32_swap_b32_e32 v101, v0
	v_max_f32_e32 v0, v0, v101
	v_cndmask_b32_e64 v0, v236, v0, s[80:81]
	v_add_f32_e32 v101, 0x40c00000, v100
	v_cmp_gt_f32_e32 vcc, v0, v101
	s_cbranch_vccz .LBB0_966
	v_max_f32_e32 v0, v0, v0
	v_max_f32_e32 v101, v100, v100
	v_max_f32_e32 v101, v101, v0
	v_sub_f32_e32 v0, v100, v101
	v_exp_f32_e32 v0, v0
	v_mov_b32_e32 v100, v101
	v_mul_f32_e32 v79, v79, v0
	v_pk_mul_f32 v[32:33], v[32:33], v[0:1] op_sel_hi:[1,0]
	v_pk_mul_f32 v[30:31], v[30:31], v[0:1] op_sel_hi:[1,0]
	v_pk_mul_f32 v[28:29], v[28:29], v[0:1] op_sel_hi:[1,0]
	v_pk_mul_f32 v[26:27], v[26:27], v[0:1] op_sel_hi:[1,0]
	v_pk_mul_f32 v[24:25], v[24:25], v[0:1] op_sel_hi:[1,0]
	v_pk_mul_f32 v[22:23], v[22:23], v[0:1] op_sel_hi:[1,0]
	v_pk_mul_f32 v[20:21], v[20:21], v[0:1] op_sel_hi:[1,0]
	v_pk_mul_f32 v[18:19], v[18:19], v[0:1] op_sel_hi:[1,0]
	v_pk_mul_f32 v[16:17], v[16:17], v[0:1] op_sel_hi:[1,0]
	v_pk_mul_f32 v[14:15], v[14:15], v[0:1] op_sel_hi:[1,0]
	v_pk_mul_f32 v[12:13], v[12:13], v[0:1] op_sel_hi:[1,0]
	v_pk_mul_f32 v[10:11], v[10:11], v[0:1] op_sel_hi:[1,0]
	v_pk_mul_f32 v[8:9], v[8:9], v[0:1] op_sel_hi:[1,0]
	v_pk_mul_f32 v[6:7], v[6:7], v[0:1] op_sel_hi:[1,0]
	v_pk_mul_f32 v[4:5], v[4:5], v[0:1] op_sel_hi:[1,0]
	v_pk_mul_f32 v[2:3], v[2:3], v[0:1] op_sel_hi:[1,0]
.LBB0_966:
	v_cndmask_b32_e64 v207, -v236, v100, s[80:81]
	v_sub_f32_e32 v50, v50, v207
	v_sub_f32_e32 v34, v34, v207
	v_exp_f32_e32 v50, v50
	v_exp_f32_e32 v34, v34
	v_sub_f32_e32 v51, v51, v207
	v_sub_f32_e32 v35, v35, v207
	v_exp_f32_e32 v51, v51
	v_exp_f32_e32 v35, v35
	v_sub_f32_e32 v52, v52, v207
	v_sub_f32_e32 v36, v36, v207
	v_exp_f32_e32 v52, v52
	v_exp_f32_e32 v36, v36
	v_sub_f32_e32 v53, v53, v207
	v_sub_f32_e32 v37, v37, v207
	v_exp_f32_e32 v53, v53
	v_exp_f32_e32 v37, v37
	v_sub_f32_e32 v54, v54, v207
	v_sub_f32_e32 v38, v38, v207
	v_exp_f32_e32 v54, v54
	v_exp_f32_e32 v38, v38
	v_sub_f32_e32 v55, v55, v207
	v_sub_f32_e32 v39, v39, v207
	v_exp_f32_e32 v55, v55
	v_exp_f32_e32 v39, v39
	v_sub_f32_e32 v56, v56, v207
	v_sub_f32_e32 v40, v40, v207
	v_exp_f32_e32 v56, v56
	v_exp_f32_e32 v40, v40
	v_sub_f32_e32 v57, v57, v207
	v_sub_f32_e32 v41, v41, v207
	v_exp_f32_e32 v57, v57
	v_exp_f32_e32 v41, v41
	v_pk_add_f32 v[102:103], v[50:51], v[34:35]
	v_pk_add_f32 v[102:103], v[102:103], v[52:53]
	v_pk_add_f32 v[102:103], v[102:103], v[36:37]
	v_pk_add_f32 v[102:103], v[102:103], v[54:55]
	v_pk_add_f32 v[102:103], v[102:103], v[38:39]
	v_pk_add_f32 v[102:103], v[102:103], v[56:57]
	v_pk_add_f32 v[102:103], v[102:103], v[40:41]
	v_cvt_pk_bf16_f32 v50, v50, v51
	v_cvt_pk_bf16_f32 v51, v52, v53
	v_cvt_pk_bf16_f32 v52, v54, v55
	v_cvt_pk_bf16_f32 v53, v56, v57
	v_cvt_pk_bf16_f32 v34, v34, v35
	v_cvt_pk_bf16_f32 v35, v36, v37
	v_cvt_pk_bf16_f32 v36, v38, v39
	v_cvt_pk_bf16_f32 v37, v40, v41
	ds_read_b64_tr_b16 v[54:55], v199 offset:15424
	ds_read_b64_tr_b16 v[56:57], v199 offset:16960
	ds_read_b64_tr_b16 v[38:39], v199 offset:12288
	ds_read_b64_tr_b16 v[40:41], v199 offset:13824
	s_waitcnt lgkmcnt(8)
	v_mfma_f32_32x32x16_bf16 v[2:17], v[250:253], v[50:53], v[2:17]
	ds_read_b64_tr_b16 v[250:251], v199 offset:18432
	ds_read_b64_tr_b16 v[252:253], v199 offset:19968
	v_sub_f32_e32 v58, v58, v207
	v_sub_f32_e32 v42, v42, v207
	v_exp_f32_e32 v58, v58
	v_exp_f32_e32 v42, v42
	v_sub_f32_e32 v59, v59, v207
	v_sub_f32_e32 v43, v43, v207
	v_exp_f32_e32 v59, v59
	v_exp_f32_e32 v43, v43
	v_sub_f32_e32 v60, v60, v207
	v_sub_f32_e32 v44, v44, v207
	v_exp_f32_e32 v60, v60
	v_exp_f32_e32 v44, v44
	v_sub_f32_e32 v61, v61, v207
	v_sub_f32_e32 v45, v45, v207
	v_exp_f32_e32 v61, v61
	v_exp_f32_e32 v45, v45
	s_waitcnt lgkmcnt(8)
	v_mfma_f32_32x32x16_bf16 v[18:33], v[104:107], v[50:53], v[18:33]
	ds_read_b64_tr_b16 v[104:105], v199 offset:12352
	ds_read_b64_tr_b16 v[106:107], v199 offset:13888
	v_sub_f32_e32 v62, v62, v207
	v_sub_f32_e32 v46, v46, v207
	v_exp_f32_e32 v62, v62
	v_exp_f32_e32 v46, v46
	v_sub_f32_e32 v63, v63, v207
	v_sub_f32_e32 v47, v47, v207
	v_exp_f32_e32 v63, v63
	v_exp_f32_e32 v47, v47
	v_sub_f32_e32 v64, v64, v207
	v_sub_f32_e32 v48, v48, v207
	v_exp_f32_e32 v64, v64
	v_exp_f32_e32 v48, v48
	v_sub_f32_e32 v65, v65, v207
	v_sub_f32_e32 v49, v49, v207
	v_exp_f32_e32 v65, v65
	v_exp_f32_e32 v49, v49
	s_waitcnt lgkmcnt(8)
	v_mfma_f32_32x32x16_bf16 v[2:17], v[108:111], v[34:37], v[2:17]
	ds_read_b64_tr_b16 v[108:109], v199 offset:18496
	ds_read_b64_tr_b16 v[110:111], v199 offset:20032
	v_pk_add_f32 v[102:103], v[102:103], v[58:59]
	v_pk_add_f32 v[102:103], v[102:103], v[42:43]
	v_pk_add_f32 v[102:103], v[102:103], v[60:61]
	v_pk_add_f32 v[102:103], v[102:103], v[44:45]
	v_pk_add_f32 v[102:103], v[102:103], v[62:63]
	v_pk_add_f32 v[102:103], v[102:103], v[46:47]
	v_pk_add_f32 v[102:103], v[102:103], v[64:65]
	v_pk_add_f32 v[102:103], v[102:103], v[48:49]
	s_waitcnt lgkmcnt(8)
	v_mfma_f32_32x32x16_bf16 v[18:33], v[54:57], v[34:37], v[18:33]
	v_cvt_pk_bf16_f32 v58, v58, v59
	v_cvt_pk_bf16_f32 v59, v60, v61
	v_cvt_pk_bf16_f32 v60, v62, v63
	v_cvt_pk_bf16_f32 v61, v64, v65
	v_cvt_pk_bf16_f32 v42, v42, v43
	v_cvt_pk_bf16_f32 v43, v44, v45
	v_cvt_pk_bf16_f32 v44, v46, v47
	v_cvt_pk_bf16_f32 v45, v48, v49
	v_add_f32_e32 v102, v102, v103
	v_mov_b32_e32 v101, v102
	s_waitcnt lgkmcnt(6)
	v_mfma_f32_32x32x16_bf16 v[2:17], v[38:41], v[58:61], v[2:17]
	v_permlane32_swap_b32_e32 v101, v102
	s_waitcnt lgkmcnt(2)
	v_mfma_f32_32x32x16_bf16 v[18:33], v[104:107], v[58:61], v[18:33]
	v_add_f32_e32 v102, v102, v101
	v_add_f32_e32 v79, v79, v102
	v_mfma_f32_32x32x16_bf16 v[2:17], v[250:253], v[42:45], v[2:17]
	s_waitcnt lgkmcnt(0)
	v_mfma_f32_32x32x16_bf16 v[18:33], v[108:111], v[42:45], v[18:33]

.LBB0_971:
	v_lshrrev_b32_e32 v0, s26, v78
	v_and_b32_e32 v0, 1, v0
	v_cmp_eq_u32_e64 s[0:1], 1, v0
	v_bfe_u32 v0, v78, s26, 1
	v_cmp_ne_u32_e32 vcc, 0, v0
	s_cbranch_vccz .LBB0_977
	v_add_u32_e32 v0, v228, v136
	ds_read_b128 v[38:41], v0
	ds_read_b128 v[34:37], v0 offset:4608
	ds_read_b128 v[102:105], v0 offset:32
	ds_read_b128 v[106:109], v0 offset:4640
	ds_read_b128 v[250:253], v0 offset:64
	s_cmp_eq_u64 vcc, -1
	s_cselect_b64 s[80:81], -1, 0
	s_cmp_lg_u32 s26, s22
	s_cselect_b64 vcc, -1, 0
	s_and_b64 s[80:81], vcc, s[80:81]
	s_and_b64 vcc, exec, s[80:81]
	v_add_u32_e32 v255, v230, v198
	s_waitcnt lgkmcnt(4)
	v_mfma_f32_32x32x16_bf16 v[50:65], v[38:41], v[80:83], 0
	s_waitcnt lgkmcnt(3)
	v_mfma_f32_32x32x16_bf16 v[34:49], v[34:37], v[80:83], 0
	s_waitcnt lgkmcnt(2)
	v_mfma_f32_32x32x16_bf16 v[50:65], v[102:105], v[84:87], v[50:65]
	ds_read_b128 v[102:105], v0 offset:4672
	s_waitcnt lgkmcnt(2)
	v_mfma_f32_32x32x16_bf16 v[34:49], v[106:109], v[84:87], v[34:49]
	ds_read_b128 v[106:109], v0 offset:96
	s_waitcnt lgkmcnt(2)
	v_mfma_f32_32x32x16_bf16 v[50:65], v[250:253], v[88:91], v[50:65]
	ds_read_b128 v[250:253], v0 offset:4704
	s_waitcnt lgkmcnt(2)
	v_mfma_f32_32x32x16_bf16 v[34:49], v[102:105], v[88:91], v[34:49]
	s_waitcnt lgkmcnt(1)
	v_mfma_f32_32x32x16_bf16 v[50:65], v[106:109], v[92:95], v[50:65]
	s_waitcnt lgkmcnt(0)
	v_mfma_f32_32x32x16_bf16 v[34:49], v[250:253], v[92:95], v[34:49]
	ds_read_b64_tr_b16 v[250:251], v255
	ds_read_b64_tr_b16 v[252:253], v255 offset:1536
	ds_read_b64_tr_b16 v[104:105], v255 offset:64
	ds_read_b64_tr_b16 v[106:107], v255 offset:1600
	ds_read_b64_tr_b16 v[108:109], v255 offset:6144
	ds_read_b64_tr_b16 v[110:111], v255 offset:7680
	s_cbranch_vccnz .Latt_nm_1
	s_cmp_eq_u32 s26, s22
	s_cbranch_scc1 .Latt_sl_1
	s_mov_b64 s[80:81], s[0:1]
	s_branch .LBB0_974
.Latt_sl_1:
	s_lshl_b32 s2, s26, 6
	v_subrev_u32_e32 v0, s2, v243
	v_subrev_u32_e32 v101, 32, v0
	v_cmp_le_i32_e32 vcc, v118, v0
	v_cmp_le_i32_e64 s[80:81], v118, v101
	s_and_b64 vcc, s[0:1], vcc
	s_nop 1
	v_cndmask_b32_e32 v50, v236, v50, vcc
	s_and_b64 vcc, s[0:1], s[80:81]
	s_nop 0
	v_cndmask_b32_e32 v34, v236, v34, vcc
	v_cmp_lt_i32_e32 vcc, v118, v0
	v_cmp_lt_i32_e64 s[80:81], v118, v101
	s_and_b64 vcc, s[0:1], vcc
	v_cndmask_b32_e32 v51, v236, v51, vcc
	s_and_b64 vcc, s[0:1], s[80:81]
	v_cndmask_b32_e32 v35, v236, v35, vcc
	v_cmp_le_i32_e32 vcc, v137, v0
	v_cmp_le_i32_e64 s[80:81], v137, v101
	s_and_b64 vcc, s[0:1], vcc
	v_cndmask_b32_e32 v52, v236, v52, vcc
	s_and_b64 vcc, s[0:1], s[80:81]
	v_cndmask_b32_e32 v36, v236, v36, vcc
	v_cmp_le_i32_e32 vcc, v138, v0
	v_cmp_le_i32_e64 s[80:81], v138, v101
	s_and_b64 vcc, s[0:1], vcc
	v_cndmask_b32_e32 v53, v236, v53, vcc
	s_and_b64 vcc, s[0:1], s[80:81]
	v_cndmask_b32_e32 v37, v236, v37, vcc
	v_cmp_le_i32_e32 vcc, v139, v0
	v_cmp_le_i32_e64 s[80:81], v139, v101
	s_and_b64 vcc, s[0:1], vcc
	v_cndmask_b32_e32 v54, v236, v54, vcc
	s_and_b64 vcc, s[0:1], s[80:81]
	v_cndmask_b32_e32 v38, v236, v38, vcc
	v_cmp_le_i32_e32 vcc, v140, v0
	v_cmp_le_i32_e64 s[80:81], v140, v101
	s_and_b64 vcc, s[0:1], vcc
	v_cndmask_b32_e32 v55, v236, v55, vcc
	s_and_b64 vcc, s[0:1], s[80:81]
	v_cndmask_b32_e32 v39, v236, v39, vcc
	v_cmp_le_i32_e32 vcc, v141, v0
	v_cmp_le_i32_e64 s[80:81], v141, v101
	s_and_b64 vcc, s[0:1], vcc
	v_cndmask_b32_e32 v56, v236, v56, vcc
	s_and_b64 vcc, s[0:1], s[80:81]
	v_cndmask_b32_e32 v40, v236, v40, vcc
	v_cmp_le_i32_e32 vcc, v142, v0
	v_cmp_le_i32_e64 s[80:81], v142, v101
	s_and_b64 vcc, s[0:1], vcc
	v_cndmask_b32_e32 v57, v236, v57, vcc
	s_and_b64 vcc, s[0:1], s[80:81]
	v_cndmask_b32_e32 v41, v236, v41, vcc
	v_cmp_le_i32_e32 vcc, v143, v0
	v_cmp_le_i32_e64 s[80:81], v143, v101
	s_and_b64 vcc, s[0:1], vcc
	v_cndmask_b32_e32 v58, v236, v58, vcc
	s_and_b64 vcc, s[0:1], s[80:81]
	v_cndmask_b32_e32 v42, v236, v42, vcc
	v_cmp_le_i32_e32 vcc, v144, v0
	v_cmp_le_i32_e64 s[80:81], v144, v101
	s_and_b64 vcc, s[0:1], vcc
	v_cndmask_b32_e32 v59, v236, v59, vcc
	s_and_b64 vcc, s[0:1], s[80:81]
	v_cndmask_b32_e32 v43, v236, v43, vcc
	v_cmp_le_i32_e32 vcc, v145, v0
	v_cmp_le_i32_e64 s[80:81], v145, v101
	s_and_b64 vcc, s[0:1], vcc
	v_cndmask_b32_e32 v60, v236, v60, vcc
	s_and_b64 vcc, s[0:1], s[80:81]
	v_cndmask_b32_e32 v44, v236, v44, vcc
	v_cmp_le_i32_e32 vcc, v146, v0
	v_cmp_le_i32_e64 s[80:81], v146, v101
	s_and_b64 vcc, s[0:1], vcc
	v_cndmask_b32_e32 v61, v236, v61, vcc
	s_and_b64 vcc, s[0:1], s[80:81]
	v_cndmask_b32_e32 v45, v236, v45, vcc
	v_cmp_le_i32_e32 vcc, v147, v0
	v_cmp_le_i32_e64 s[80:81], v147, v101
	s_and_b64 vcc, s[0:1], vcc
	v_cndmask_b32_e32 v62, v236, v62, vcc
	s_and_b64 vcc, s[0:1], s[80:81]
	v_cndmask_b32_e32 v46, v236, v46, vcc
	v_cmp_le_i32_e32 vcc, v148, v0
	v_cmp_le_i32_e64 s[80:81], v148, v101
	s_and_b64 vcc, s[0:1], vcc
	v_cndmask_b32_e32 v63, v236, v63, vcc
	s_and_b64 vcc, s[0:1], s[80:81]
	v_cndmask_b32_e32 v47, v236, v47, vcc
	v_cmp_le_i32_e32 vcc, v149, v0
	v_cmp_le_i32_e64 s[80:81], v149, v101
	s_and_b64 vcc, s[0:1], vcc
	v_cndmask_b32_e32 v64, v236, v64, vcc
	s_and_b64 vcc, s[0:1], s[80:81]
	v_cndmask_b32_e32 v48, v236, v48, vcc
	v_cmp_le_i32_e32 vcc, v150, v0
	v_cmp_le_i32_e64 s[80:81], v150, v101
	s_and_b64 vcc, s[0:1], vcc
	v_cndmask_b32_e32 v65, v236, v65, vcc
	s_and_b64 vcc, s[0:1], s[80:81]
	v_cndmask_b32_e32 v49, v236, v49, vcc
	s_mov_b64 s[80:81], -1
	s_branch .LBB0_974

.LBB0_976:
	v_cndmask_b32_e64 v207, -v236, v100, s[80:81]
	v_sub_f32_e32 v50, v50, v207
	v_sub_f32_e32 v34, v34, v207
	v_exp_f32_e32 v50, v50
	v_exp_f32_e32 v34, v34
	v_sub_f32_e32 v51, v51, v207
	v_sub_f32_e32 v35, v35, v207
	v_exp_f32_e32 v51, v51
	v_exp_f32_e32 v35, v35
	v_sub_f32_e32 v52, v52, v207
	v_sub_f32_e32 v36, v36, v207
	v_exp_f32_e32 v52, v52
	v_exp_f32_e32 v36, v36
	v_sub_f32_e32 v53, v53, v207
	v_sub_f32_e32 v37, v37, v207
	v_exp_f32_e32 v53, v53
	v_exp_f32_e32 v37, v37
	v_sub_f32_e32 v54, v54, v207
	v_sub_f32_e32 v38, v38, v207
	v_exp_f32_e32 v54, v54
	v_exp_f32_e32 v38, v38
	v_sub_f32_e32 v55, v55, v207
	v_sub_f32_e32 v39, v39, v207
	v_exp_f32_e32 v55, v55
	v_exp_f32_e32 v39, v39
	v_sub_f32_e32 v56, v56, v207
	v_sub_f32_e32 v40, v40, v207
	v_exp_f32_e32 v56, v56
	v_exp_f32_e32 v40, v40
	v_sub_f32_e32 v57, v57, v207
	v_sub_f32_e32 v41, v41, v207
	v_exp_f32_e32 v57, v57
	v_exp_f32_e32 v41, v41
	v_pk_add_f32 v[102:103], v[50:51], v[34:35]
	v_pk_add_f32 v[102:103], v[102:103], v[52:53]
	v_pk_add_f32 v[102:103], v[102:103], v[36:37]
	v_pk_add_f32 v[102:103], v[102:103], v[54:55]
	v_pk_add_f32 v[102:103], v[102:103], v[38:39]
	v_pk_add_f32 v[102:103], v[102:103], v[56:57]
	v_pk_add_f32 v[102:103], v[102:103], v[40:41]
	v_cvt_pk_bf16_f32 v50, v50, v51
	v_cvt_pk_bf16_f32 v51, v52, v53
	v_cvt_pk_bf16_f32 v52, v54, v55
	v_cvt_pk_bf16_f32 v53, v56, v57
	v_cvt_pk_bf16_f32 v34, v34, v35
	v_cvt_pk_bf16_f32 v35, v36, v37
	v_cvt_pk_bf16_f32 v36, v38, v39
	v_cvt_pk_bf16_f32 v37, v40, v41
	ds_read_b64_tr_b16 v[54:55], v255 offset:6208
	ds_read_b64_tr_b16 v[56:57], v255 offset:7744
	ds_read_b64_tr_b16 v[38:39], v255 offset:3072
	ds_read_b64_tr_b16 v[40:41], v255 offset:4608
	s_waitcnt lgkmcnt(8)
	v_mfma_f32_32x32x16_bf16 v[2:17], v[250:253], v[50:53], v[2:17]
	ds_read_b64_tr_b16 v[250:251], v255 offset:9216
	ds_read_b64_tr_b16 v[252:253], v255 offset:10752
	v_sub_f32_e32 v58, v58, v207
	v_sub_f32_e32 v42, v42, v207
	v_exp_f32_e32 v58, v58
	v_exp_f32_e32 v42, v42
	v_sub_f32_e32 v59, v59, v207
	v_sub_f32_e32 v43, v43, v207
	v_exp_f32_e32 v59, v59
	v_exp_f32_e32 v43, v43
	v_sub_f32_e32 v60, v60, v207
	v_sub_f32_e32 v44, v44, v207
	v_exp_f32_e32 v60, v60
	v_exp_f32_e32 v44, v44
	v_sub_f32_e32 v61, v61, v207
	v_sub_f32_e32 v45, v45, v207
	v_exp_f32_e32 v61, v61
	v_exp_f32_e32 v45, v45
	s_waitcnt lgkmcnt(8)
	v_mfma_f32_32x32x16_bf16 v[18:33], v[104:107], v[50:53], v[18:33]
	ds_read_b64_tr_b16 v[104:105], v255 offset:3136
	ds_read_b64_tr_b16 v[106:107], v255 offset:4672
	v_sub_f32_e32 v62, v62, v207
	v_sub_f32_e32 v46, v46, v207
	v_exp_f32_e32 v62, v62
	v_exp_f32_e32 v46, v46
	v_sub_f32_e32 v63, v63, v207
	v_sub_f32_e32 v47, v47, v207
	v_exp_f32_e32 v63, v63
	v_exp_f32_e32 v47, v47
	v_sub_f32_e32 v64, v64, v207
	v_sub_f32_e32 v48, v48, v207
	v_exp_f32_e32 v64, v64
	v_exp_f32_e32 v48, v48
	v_sub_f32_e32 v65, v65, v207
	v_sub_f32_e32 v49, v49, v207
	v_exp_f32_e32 v65, v65
	v_exp_f32_e32 v49, v49
	s_waitcnt lgkmcnt(8)
	v_mfma_f32_32x32x16_bf16 v[2:17], v[108:111], v[34:37], v[2:17]
	ds_read_b64_tr_b16 v[108:109], v255 offset:9280
	ds_read_b64_tr_b16 v[110:111], v255 offset:10816
	v_pk_add_f32 v[102:103], v[102:103], v[58:59]
	v_pk_add_f32 v[102:103], v[102:103], v[42:43]
	v_pk_add_f32 v[102:103], v[102:103], v[60:61]
	v_pk_add_f32 v[102:103], v[102:103], v[44:45]
	v_pk_add_f32 v[102:103], v[102:103], v[62:63]
	v_pk_add_f32 v[102:103], v[102:103], v[46:47]
	v_pk_add_f32 v[102:103], v[102:103], v[64:65]
	v_pk_add_f32 v[102:103], v[102:103], v[48:49]
	s_waitcnt lgkmcnt(8)
	v_mfma_f32_32x32x16_bf16 v[18:33], v[54:57], v[34:37], v[18:33]
	v_cvt_pk_bf16_f32 v58, v58, v59
	v_cvt_pk_bf16_f32 v59, v60, v61
	v_cvt_pk_bf16_f32 v60, v62, v63
	v_cvt_pk_bf16_f32 v61, v64, v65
	v_cvt_pk_bf16_f32 v42, v42, v43
	v_cvt_pk_bf16_f32 v43, v44, v45
	v_cvt_pk_bf16_f32 v44, v46, v47
	v_cvt_pk_bf16_f32 v45, v48, v49
	v_add_f32_e32 v102, v102, v103
	v_mov_b32_e32 v101, v102
	s_waitcnt lgkmcnt(6)
	v_mfma_f32_32x32x16_bf16 v[2:17], v[38:41], v[58:61], v[2:17]
	v_permlane32_swap_b32_e32 v101, v102
	s_waitcnt lgkmcnt(2)
	v_mfma_f32_32x32x16_bf16 v[18:33], v[104:107], v[58:61], v[18:33]
	v_add_f32_e32 v102, v102, v101
	v_add_f32_e32 v79, v79, v102
	v_mfma_f32_32x32x16_bf16 v[2:17], v[250:253], v[42:45], v[2:17]
	s_waitcnt lgkmcnt(0)
	v_mfma_f32_32x32x16_bf16 v[18:33], v[108:111], v[42:45], v[18:33]

.LBB0_988:
	ds_read_b128 v[52:55], v242
	ds_read_b128 v[48:51], v242 offset:4608
	ds_read_b128 v[2:5], v242 offset:32
	ds_read_b128 v[6:9], v242 offset:4640
	ds_read_b128 v[250:253], v242 offset:64
	s_cmp_eq_u32 s27, s22
	s_cselect_b64 s[0:1], -1, 0
	s_cmp_eq_u32 s27, s79
	s_cselect_b64 s[28:29], -1, 0
	s_or_b64 s[0:1], s[0:1], s[28:29]
	s_andn2_b64 vcc, exec, s[0:1]
	s_waitcnt lgkmcnt(4)
	v_mfma_f32_32x32x16_bf16 v[64:79], v[52:55], v[80:83], 0
	s_waitcnt lgkmcnt(3)
	v_mfma_f32_32x32x16_bf16 v[48:63], v[48:51], v[80:83], 0
	s_waitcnt lgkmcnt(2)
	v_mfma_f32_32x32x16_bf16 v[64:79], v[2:5], v[84:87], v[64:79]
	ds_read_b128 v[2:5], v242 offset:4672
	s_waitcnt lgkmcnt(2)
	v_mfma_f32_32x32x16_bf16 v[48:63], v[6:9], v[84:87], v[48:63]
	ds_read_b128 v[6:9], v242 offset:96
	s_waitcnt lgkmcnt(2)
	v_mfma_f32_32x32x16_bf16 v[64:79], v[250:253], v[88:91], v[64:79]
	ds_read_b128 v[250:253], v242 offset:4704
	s_waitcnt lgkmcnt(2)
	v_mfma_f32_32x32x16_bf16 v[48:63], v[2:5], v[88:91], v[48:63]
	s_waitcnt lgkmcnt(1)
	v_mfma_f32_32x32x16_bf16 v[64:79], v[6:9], v[92:95], v[64:79]
	s_waitcnt lgkmcnt(0)
	v_mfma_f32_32x32x16_bf16 v[48:63], v[250:253], v[92:95], v[48:63]
	ds_read_b64_tr_b16 v[250:251], v199 offset:9216
	ds_read_b64_tr_b16 v[252:253], v199 offset:10752
	ds_read_b64_tr_b16 v[6:7], v199 offset:9280
	ds_read_b64_tr_b16 v[8:9], v199 offset:10816
	ds_read_b64_tr_b16 v[10:11], v199 offset:15360
	ds_read_b64_tr_b16 v[12:13], v199 offset:16896
	s_cbranch_vccnz .LBB0_990
	s_lshl_b32 s0, s27, 6
	v_subrev_u32_e32 v0, s0, v243
	v_add_u32_e32 v2, 0xfffffe00, v0
	v_cmp_le_i32_e32 vcc, v118, v0
	v_cmp_gt_i32_e64 s[0:1], v118, v2
	s_and_b64 vcc, vcc, s[0:1]
	v_cmp_le_i32_e64 s[0:1], v151, v0
	v_cmp_gt_i32_e64 s[80:81], v151, v2
	s_and_b64 s[0:1], s[0:1], s[80:81]
	v_cndmask_b32_e32 v64, v236, v64, vcc
	s_nop 0
	v_cndmask_b32_e64 v48, v236, v48, s[0:1]
	v_cmp_lt_i32_e32 vcc, v118, v0
	v_cmp_ge_i32_e64 s[0:1], v118, v2
	s_and_b64 vcc, vcc, s[0:1]
	v_cmp_le_i32_e64 s[0:1], v231, v0
	v_cmp_gt_i32_e64 s[80:81], v231, v2
	s_and_b64 s[0:1], s[0:1], s[80:81]
	v_cndmask_b32_e32 v65, v236, v65, vcc
	v_cndmask_b32_e64 v49, v236, v49, s[0:1]
	v_cmp_le_i32_e32 vcc, v137, v0
	v_cmp_gt_i32_e64 s[0:1], v137, v2
	s_and_b64 vcc, vcc, s[0:1]
	v_cmp_le_i32_e64 s[0:1], v152, v0
	v_cmp_gt_i32_e64 s[80:81], v152, v2
	s_and_b64 s[0:1], s[0:1], s[80:81]
	v_cndmask_b32_e32 v66, v236, v66, vcc
	v_cndmask_b32_e64 v50, v236, v50, s[0:1]
	v_cmp_le_i32_e32 vcc, v138, v0
	v_cmp_gt_i32_e64 s[0:1], v138, v2
	s_and_b64 vcc, vcc, s[0:1]
	v_cmp_le_i32_e64 s[0:1], v153, v0
	v_cmp_gt_i32_e64 s[80:81], v153, v2
	s_and_b64 s[0:1], s[0:1], s[80:81]
	v_cndmask_b32_e32 v67, v236, v67, vcc
	v_cndmask_b32_e64 v51, v236, v51, s[0:1]
	v_cmp_le_i32_e32 vcc, v139, v0
	v_cmp_gt_i32_e64 s[0:1], v139, v2
	s_and_b64 vcc, vcc, s[0:1]
	v_cmp_le_i32_e64 s[0:1], v154, v0
	v_cmp_gt_i32_e64 s[80:81], v154, v2
	s_and_b64 s[0:1], s[0:1], s[80:81]
	v_cndmask_b32_e32 v68, v236, v68, vcc
	v_cndmask_b32_e64 v52, v236, v52, s[0:1]
	v_cmp_le_i32_e32 vcc, v140, v0
	v_cmp_gt_i32_e64 s[0:1], v140, v2
	s_and_b64 vcc, vcc, s[0:1]
	v_cmp_le_i32_e64 s[0:1], v155, v0
	v_cmp_gt_i32_e64 s[80:81], v155, v2
	s_and_b64 s[0:1], s[0:1], s[80:81]
	v_cndmask_b32_e32 v69, v236, v69, vcc
	v_cndmask_b32_e64 v53, v236, v53, s[0:1]
	v_cmp_le_i32_e32 vcc, v141, v0
	v_cmp_gt_i32_e64 s[0:1], v141, v2
	s_and_b64 vcc, vcc, s[0:1]
	v_cmp_le_i32_e64 s[0:1], v156, v0
	v_cmp_gt_i32_e64 s[80:81], v156, v2
	s_and_b64 s[0:1], s[0:1], s[80:81]
	v_cndmask_b32_e32 v70, v236, v70, vcc
	v_cndmask_b32_e64 v54, v236, v54, s[0:1]
	v_cmp_le_i32_e32 vcc, v142, v0
	v_cmp_gt_i32_e64 s[0:1], v142, v2
	s_and_b64 vcc, vcc, s[0:1]
	v_cmp_le_i32_e64 s[0:1], v157, v0
	v_cmp_gt_i32_e64 s[80:81], v157, v2
	s_and_b64 s[0:1], s[0:1], s[80:81]
	v_cndmask_b32_e32 v71, v236, v71, vcc
	v_cndmask_b32_e64 v55, v236, v55, s[0:1]
	v_cmp_le_i32_e32 vcc, v143, v0
	v_cmp_gt_i32_e64 s[0:1], v143, v2
	s_and_b64 vcc, vcc, s[0:1]
	v_cmp_le_i32_e64 s[0:1], v158, v0
	v_cmp_gt_i32_e64 s[80:81], v158, v2
	s_and_b64 s[0:1], s[0:1], s[80:81]
	v_cndmask_b32_e32 v72, v236, v72, vcc
	v_cndmask_b32_e64 v56, v236, v56, s[0:1]
	v_cmp_le_i32_e32 vcc, v144, v0
	v_cmp_gt_i32_e64 s[0:1], v144, v2
	s_and_b64 vcc, vcc, s[0:1]
	v_cmp_le_i32_e64 s[0:1], v159, v0
	v_cmp_gt_i32_e64 s[80:81], v159, v2
	s_and_b64 s[0:1], s[0:1], s[80:81]
	v_cndmask_b32_e32 v73, v236, v73, vcc
	v_cndmask_b32_e64 v57, v236, v57, s[0:1]
	v_cmp_le_i32_e32 vcc, v145, v0
	v_cmp_gt_i32_e64 s[0:1], v145, v2
	s_and_b64 vcc, vcc, s[0:1]
	v_cmp_le_i32_e64 s[0:1], v160, v0
	v_cmp_gt_i32_e64 s[80:81], v160, v2
	s_and_b64 s[0:1], s[0:1], s[80:81]
	v_cndmask_b32_e32 v74, v236, v74, vcc
	v_cndmask_b32_e64 v58, v236, v58, s[0:1]
	v_cmp_le_i32_e32 vcc, v146, v0
	v_cmp_gt_i32_e64 s[0:1], v146, v2
	s_and_b64 vcc, vcc, s[0:1]
	v_cmp_le_i32_e64 s[0:1], v161, v0
	v_cmp_gt_i32_e64 s[80:81], v161, v2
	s_and_b64 s[0:1], s[0:1], s[80:81]
	v_cndmask_b32_e32 v75, v236, v75, vcc
	v_cndmask_b32_e64 v59, v236, v59, s[0:1]
	v_cmp_le_i32_e32 vcc, v147, v0
	v_cmp_gt_i32_e64 s[0:1], v147, v2
	s_and_b64 vcc, vcc, s[0:1]
	v_cmp_le_i32_e64 s[0:1], v162, v0
	v_cmp_gt_i32_e64 s[80:81], v162, v2
	s_and_b64 s[0:1], s[0:1], s[80:81]
	v_cndmask_b32_e32 v76, v236, v76, vcc
	v_cndmask_b32_e64 v60, v236, v60, s[0:1]
	v_cmp_le_i32_e32 vcc, v148, v0
	v_cmp_gt_i32_e64 s[0:1], v148, v2
	s_and_b64 vcc, vcc, s[0:1]
	v_cmp_le_i32_e64 s[0:1], v163, v0
	v_cmp_gt_i32_e64 s[80:81], v163, v2
	s_and_b64 s[0:1], s[0:1], s[80:81]
	v_cndmask_b32_e32 v77, v236, v77, vcc
	v_cndmask_b32_e64 v61, v236, v61, s[0:1]
	v_cmp_le_i32_e32 vcc, v149, v0
	v_cmp_gt_i32_e64 s[0:1], v149, v2
	s_and_b64 vcc, vcc, s[0:1]
	v_cmp_le_i32_e64 s[0:1], v164, v0
	v_cmp_gt_i32_e64 s[80:81], v164, v2
	s_and_b64 s[0:1], s[0:1], s[80:81]
	v_cndmask_b32_e32 v78, v236, v78, vcc
	v_cndmask_b32_e64 v62, v236, v62, s[0:1]
	v_cmp_le_i32_e32 vcc, v150, v0
	v_cmp_gt_i32_e64 s[0:1], v150, v2
	s_and_b64 vcc, vcc, s[0:1]
	v_cmp_le_i32_e64 s[0:1], v165, v0
	v_cmp_gt_i32_e64 s[80:81], v165, v2
	s_and_b64 s[0:1], s[0:1], s[80:81]
	v_cndmask_b32_e32 v79, v236, v79, vcc
	v_cndmask_b32_e64 v63, v236, v63, s[0:1]
.LBB0_990:
	s_nop 10
	v_max3_f32 v0, v64, v48, v65
	v_max3_f32 v2, v49, v66, v50
	v_max3_f32 v3, v67, v51, v68
	v_max3_f32 v4, v52, v69, v53
	v_max3_f32 v0, v0, v70, v54
	v_max3_f32 v2, v2, v71, v55
	v_max3_f32 v3, v3, v72, v56
	v_max3_f32 v4, v4, v73, v57
	v_max3_f32 v0, v0, v74, v58
	v_max3_f32 v2, v2, v75, v59
	v_max3_f32 v3, v3, v76, v60
	v_max3_f32 v4, v4, v77, v61
	v_max3_f32 v0, v0, v78, v62
	v_max3_f32 v2, v2, v79, v63
	v_max3_f32 v0, v0, v3, v4
	v_max_f32_e32 v0, v0, v2
	v_mov_b32_e32 v2, v0
	s_nop 1
	v_permlane32_swap_b32_e32 v2, v0
	v_max_f32_e32 v0, v0, v2
	v_add_f32_e32 v2, 0x40c00000, v245
	v_cmp_gt_f32_e32 vcc, v0, v2
	s_cbranch_vccz .LBB0_992
	v_max_f32_e32 v0, v0, v0
	v_max_f32_e32 v2, v245, v245
	v_max_f32_e32 v2, v2, v0
	v_sub_f32_e32 v0, v245, v2
	v_exp_f32_e32 v0, v0
	v_mov_b32_e32 v245, v2
	v_mul_f32_e32 v244, v244, v0
	v_pk_mul_f32 v[46:47], v[46:47], v[0:1] op_sel_hi:[1,0]
	v_pk_mul_f32 v[44:45], v[44:45], v[0:1] op_sel_hi:[1,0]
	v_pk_mul_f32 v[42:43], v[42:43], v[0:1] op_sel_hi:[1,0]
	v_pk_mul_f32 v[40:41], v[40:41], v[0:1] op_sel_hi:[1,0]
	v_pk_mul_f32 v[38:39], v[38:39], v[0:1] op_sel_hi:[1,0]
	v_pk_mul_f32 v[36:37], v[36:37], v[0:1] op_sel_hi:[1,0]
	v_pk_mul_f32 v[34:35], v[34:35], v[0:1] op_sel_hi:[1,0]
	v_pk_mul_f32 v[32:33], v[32:33], v[0:1] op_sel_hi:[1,0]
	v_pk_mul_f32 v[30:31], v[30:31], v[0:1] op_sel_hi:[1,0]
	v_pk_mul_f32 v[28:29], v[28:29], v[0:1] op_sel_hi:[1,0]
	v_pk_mul_f32 v[26:27], v[26:27], v[0:1] op_sel_hi:[1,0]
	v_pk_mul_f32 v[24:25], v[24:25], v[0:1] op_sel_hi:[1,0]
	v_pk_mul_f32 v[22:23], v[22:23], v[0:1] op_sel_hi:[1,0]
	v_pk_mul_f32 v[20:21], v[20:21], v[0:1] op_sel_hi:[1,0]
	v_pk_mul_f32 v[18:19], v[18:19], v[0:1] op_sel_hi:[1,0]
	v_pk_mul_f32 v[16:17], v[16:17], v[0:1] op_sel_hi:[1,0]
.LBB0_992:
	s_mov_b64 s[0:1], -1
	s_cmp_lt_i32 s24, 0
	v_sub_f32_e32 v64, v64, v245
	v_sub_f32_e32 v48, v48, v245
	v_exp_f32_e32 v64, v64
	v_exp_f32_e32 v48, v48
	v_sub_f32_e32 v65, v65, v245
	v_sub_f32_e32 v49, v49, v245
	v_exp_f32_e32 v65, v65
	v_exp_f32_e32 v49, v49
	v_sub_f32_e32 v66, v66, v245
	v_sub_f32_e32 v50, v50, v245
	v_exp_f32_e32 v66, v66
	v_exp_f32_e32 v50, v50
	v_sub_f32_e32 v67, v67, v245
	v_sub_f32_e32 v51, v51, v245
	v_exp_f32_e32 v67, v67
	v_exp_f32_e32 v51, v51
	v_sub_f32_e32 v68, v68, v245
	v_sub_f32_e32 v52, v52, v245
	v_exp_f32_e32 v68, v68
	v_exp_f32_e32 v52, v52
	v_sub_f32_e32 v69, v69, v245
	v_sub_f32_e32 v53, v53, v245
	v_exp_f32_e32 v69, v69
	v_exp_f32_e32 v53, v53
	v_sub_f32_e32 v70, v70, v245
	v_sub_f32_e32 v54, v54, v245
	v_exp_f32_e32 v70, v70
	v_exp_f32_e32 v54, v54
	v_sub_f32_e32 v71, v71, v245
	v_sub_f32_e32 v55, v55, v245
	v_exp_f32_e32 v71, v71
	v_exp_f32_e32 v55, v55
	v_pk_add_f32 v[2:3], v[64:65], v[48:49]
	v_pk_add_f32 v[2:3], v[2:3], v[66:67]
	v_pk_add_f32 v[2:3], v[2:3], v[50:51]
	v_pk_add_f32 v[2:3], v[2:3], v[68:69]
	v_pk_add_f32 v[2:3], v[2:3], v[52:53]
	v_pk_add_f32 v[2:3], v[2:3], v[70:71]
	v_pk_add_f32 v[2:3], v[2:3], v[54:55]
	v_cvt_pk_bf16_f32 v64, v64, v65
	v_cvt_pk_bf16_f32 v65, v66, v67
	v_cvt_pk_bf16_f32 v66, v68, v69
	v_cvt_pk_bf16_f32 v67, v70, v71
	v_cvt_pk_bf16_f32 v48, v48, v49
	v_cvt_pk_bf16_f32 v49, v50, v51
	v_cvt_pk_bf16_f32 v50, v52, v53
	v_cvt_pk_bf16_f32 v51, v54, v55
	ds_read_b64_tr_b16 v[68:69], v199 offset:15424
	ds_read_b64_tr_b16 v[70:71], v199 offset:16960
	ds_read_b64_tr_b16 v[52:53], v199 offset:12288
	ds_read_b64_tr_b16 v[54:55], v199 offset:13824
	s_waitcnt lgkmcnt(8)
	v_mfma_f32_32x32x16_bf16 v[32:47], v[250:253], v[64:67], v[32:47]
	ds_read_b64_tr_b16 v[250:251], v199 offset:18432
	ds_read_b64_tr_b16 v[252:253], v199 offset:19968
	v_sub_f32_e32 v72, v72, v245
	v_sub_f32_e32 v56, v56, v245
	v_exp_f32_e32 v72, v72
	v_exp_f32_e32 v56, v56
	v_sub_f32_e32 v73, v73, v245
	v_sub_f32_e32 v57, v57, v245
	v_exp_f32_e32 v73, v73
	v_exp_f32_e32 v57, v57
	v_sub_f32_e32 v74, v74, v245
	v_sub_f32_e32 v58, v58, v245
	v_exp_f32_e32 v74, v74
	v_exp_f32_e32 v58, v58
	v_sub_f32_e32 v75, v75, v245
	v_sub_f32_e32 v59, v59, v245
	v_exp_f32_e32 v75, v75
	v_exp_f32_e32 v59, v59
	s_waitcnt lgkmcnt(8)
	v_mfma_f32_32x32x16_bf16 v[16:31], v[6:9], v[64:67], v[16:31]
	ds_read_b64_tr_b16 v[6:7], v199 offset:12352
	ds_read_b64_tr_b16 v[8:9], v199 offset:13888
	v_sub_f32_e32 v76, v76, v245
	v_sub_f32_e32 v60, v60, v245
	v_exp_f32_e32 v76, v76
	v_exp_f32_e32 v60, v60
	v_sub_f32_e32 v77, v77, v245
	v_sub_f32_e32 v61, v61, v245
	v_exp_f32_e32 v77, v77
	v_exp_f32_e32 v61, v61
	v_sub_f32_e32 v78, v78, v245
	v_sub_f32_e32 v62, v62, v245
	v_exp_f32_e32 v78, v78
	v_exp_f32_e32 v62, v62
	v_sub_f32_e32 v79, v79, v245
	v_sub_f32_e32 v63, v63, v245
	v_exp_f32_e32 v79, v79
	v_exp_f32_e32 v63, v63
	s_waitcnt lgkmcnt(8)
	v_mfma_f32_32x32x16_bf16 v[32:47], v[10:13], v[48:51], v[32:47]
	ds_read_b64_tr_b16 v[10:11], v199 offset:18496
	ds_read_b64_tr_b16 v[12:13], v199 offset:20032
	v_pk_add_f32 v[2:3], v[2:3], v[72:73]
	v_pk_add_f32 v[2:3], v[2:3], v[56:57]
	v_pk_add_f32 v[2:3], v[2:3], v[74:75]
	v_pk_add_f32 v[2:3], v[2:3], v[58:59]
	v_pk_add_f32 v[2:3], v[2:3], v[76:77]
	v_pk_add_f32 v[2:3], v[2:3], v[60:61]
	v_pk_add_f32 v[2:3], v[2:3], v[78:79]
	v_pk_add_f32 v[2:3], v[2:3], v[62:63]
	s_waitcnt lgkmcnt(8)
	v_mfma_f32_32x32x16_bf16 v[16:31], v[68:71], v[48:51], v[16:31]
	v_cvt_pk_bf16_f32 v72, v72, v73
	v_cvt_pk_bf16_f32 v73, v74, v75
	v_cvt_pk_bf16_f32 v74, v76, v77
	v_cvt_pk_bf16_f32 v75, v78, v79
	v_cvt_pk_bf16_f32 v56, v56, v57
	v_cvt_pk_bf16_f32 v57, v58, v59
	v_cvt_pk_bf16_f32 v58, v60, v61
	v_cvt_pk_bf16_f32 v59, v62, v63
	v_add_f32_e32 v2, v2, v3
	v_mov_b32_e32 v4, v2
	s_waitcnt lgkmcnt(6)
	v_mfma_f32_32x32x16_bf16 v[32:47], v[52:55], v[72:75], v[32:47]
	v_permlane32_swap_b32_e32 v4, v2
	s_waitcnt lgkmcnt(2)
	v_mfma_f32_32x32x16_bf16 v[16:31], v[6:9], v[72:75], v[16:31]
	v_add_f32_e32 v2, v2, v4
	v_add_f32_e32 v244, v244, v2
	v_mfma_f32_32x32x16_bf16 v[32:47], v[250:253], v[56:59], v[32:47]
	s_waitcnt lgkmcnt(0)
	v_mfma_f32_32x32x16_bf16 v[16:31], v[10:13], v[56:59], v[16:31]
	s_cbranch_scc1 .LBB0_984
	s_and_b32 s25, s26, s25
	v_sub_co_u32_e64 v0, s[92:93], s25, 1
	s_nop 0
	v_readfirstlane_b32 s26, v0
	s_cmp_lt_i32 s23, 0
	s_ff1_i32_b32 s27, s25
	s_barrier
	s_cbranch_scc1 .LBB0_996
	s_xor_b64 s[0:1], s[92:93], -1
	s_andn2_b64 vcc, exec, s[0:1]
	s_waitcnt vmcnt(1)
	ds_write_b128 v129, v[96:99]
	s_waitcnt vmcnt(0)
	ds_write_b128 v239, v[100:103] offset:9216
	s_cbranch_vccnz .LBB0_996
	s_mul_i32 s2, s27, 0x18000
	v_lshl_add_u64 v[2:3], v[132:133], 0, s[2:3]
	global_load_dwordx4 v[96:99], v[2:3], off offset:1024
	global_load_dwordx4 v[100:103], v[2:3], off offset:1280
.LBB0_996:
	v_add_u32_e32 v0, v228, v136
	ds_read_b128 v[52:55], v0
	ds_read_b128 v[48:51], v0 offset:4608
	ds_read_b128 v[2:5], v0 offset:32
	ds_read_b128 v[6:9], v0 offset:4640
	ds_read_b128 v[250:253], v0 offset:64
	s_cmp_eq_u32 s24, s22
	s_cselect_b64 s[0:1], -1, 0
	s_cmp_eq_u32 s24, s79
	s_cselect_b64 s[28:29], -1, 0
	s_or_b64 s[0:1], s[0:1], s[28:29]
	s_andn2_b64 vcc, exec, s[0:1]
	v_add_u32_e32 v255, v230, v198
	s_waitcnt lgkmcnt(4)
	v_mfma_f32_32x32x16_bf16 v[64:79], v[52:55], v[80:83], 0
	s_waitcnt lgkmcnt(3)
	v_mfma_f32_32x32x16_bf16 v[48:63], v[48:51], v[80:83], 0
	s_waitcnt lgkmcnt(2)
	v_mfma_f32_32x32x16_bf16 v[64:79], v[2:5], v[84:87], v[64:79]
	ds_read_b128 v[2:5], v0 offset:4672
	s_waitcnt lgkmcnt(2)
	v_mfma_f32_32x32x16_bf16 v[48:63], v[6:9], v[84:87], v[48:63]
	ds_read_b128 v[6:9], v0 offset:96
	s_waitcnt lgkmcnt(2)
	v_mfma_f32_32x32x16_bf16 v[64:79], v[250:253], v[88:91], v[64:79]
	ds_read_b128 v[250:253], v0 offset:4704
	s_waitcnt lgkmcnt(2)
	v_mfma_f32_32x32x16_bf16 v[48:63], v[2:5], v[88:91], v[48:63]
	s_waitcnt lgkmcnt(1)
	v_mfma_f32_32x32x16_bf16 v[64:79], v[6:9], v[92:95], v[64:79]
	s_waitcnt lgkmcnt(0)
	v_mfma_f32_32x32x16_bf16 v[48:63], v[250:253], v[92:95], v[48:63]
	ds_read_b64_tr_b16 v[250:251], v255
	ds_read_b64_tr_b16 v[252:253], v255 offset:1536
	ds_read_b64_tr_b16 v[6:7], v255 offset:64
	ds_read_b64_tr_b16 v[8:9], v255 offset:1600
	ds_read_b64_tr_b16 v[10:11], v255 offset:6144
	ds_read_b64_tr_b16 v[12:13], v255 offset:7680
	s_cbranch_vccnz .LBB0_998
	s_lshl_b32 s0, s24, 6
	v_subrev_u32_e32 v0, s0, v243
	v_add_u32_e32 v2, 0xfffffe00, v0
	v_cmp_le_i32_e32 vcc, v118, v0
	v_cmp_gt_i32_e64 s[0:1], v118, v2
	s_and_b64 vcc, vcc, s[0:1]
	v_cmp_le_i32_e64 s[0:1], v151, v0
	v_cmp_gt_i32_e64 s[80:81], v151, v2
	s_and_b64 s[0:1], s[0:1], s[80:81]
	v_cndmask_b32_e32 v64, v236, v64, vcc
	s_nop 0
	v_cndmask_b32_e64 v48, v236, v48, s[0:1]
	v_cmp_lt_i32_e32 vcc, v118, v0
	v_cmp_ge_i32_e64 s[0:1], v118, v2
	s_and_b64 vcc, vcc, s[0:1]
	v_cmp_le_i32_e64 s[0:1], v231, v0
	v_cmp_gt_i32_e64 s[80:81], v231, v2
	s_and_b64 s[0:1], s[0:1], s[80:81]
	v_cndmask_b32_e32 v65, v236, v65, vcc
	v_cndmask_b32_e64 v49, v236, v49, s[0:1]
	v_cmp_le_i32_e32 vcc, v137, v0
	v_cmp_gt_i32_e64 s[0:1], v137, v2
	s_and_b64 vcc, vcc, s[0:1]
	v_cmp_le_i32_e64 s[0:1], v152, v0
	v_cmp_gt_i32_e64 s[80:81], v152, v2
	s_and_b64 s[0:1], s[0:1], s[80:81]
	v_cndmask_b32_e32 v66, v236, v66, vcc
	v_cndmask_b32_e64 v50, v236, v50, s[0:1]
	v_cmp_le_i32_e32 vcc, v138, v0
	v_cmp_gt_i32_e64 s[0:1], v138, v2
	s_and_b64 vcc, vcc, s[0:1]
	v_cmp_le_i32_e64 s[0:1], v153, v0
	v_cmp_gt_i32_e64 s[80:81], v153, v2
	s_and_b64 s[0:1], s[0:1], s[80:81]
	v_cndmask_b32_e32 v67, v236, v67, vcc
	v_cndmask_b32_e64 v51, v236, v51, s[0:1]
	v_cmp_le_i32_e32 vcc, v139, v0
	v_cmp_gt_i32_e64 s[0:1], v139, v2
	s_and_b64 vcc, vcc, s[0:1]
	v_cmp_le_i32_e64 s[0:1], v154, v0
	v_cmp_gt_i32_e64 s[80:81], v154, v2
	s_and_b64 s[0:1], s[0:1], s[80:81]
	v_cndmask_b32_e32 v68, v236, v68, vcc
	v_cndmask_b32_e64 v52, v236, v52, s[0:1]
	v_cmp_le_i32_e32 vcc, v140, v0
	v_cmp_gt_i32_e64 s[0:1], v140, v2
	s_and_b64 vcc, vcc, s[0:1]
	v_cmp_le_i32_e64 s[0:1], v155, v0
	v_cmp_gt_i32_e64 s[80:81], v155, v2
	s_and_b64 s[0:1], s[0:1], s[80:81]
	v_cndmask_b32_e32 v69, v236, v69, vcc
	v_cndmask_b32_e64 v53, v236, v53, s[0:1]
	v_cmp_le_i32_e32 vcc, v141, v0
	v_cmp_gt_i32_e64 s[0:1], v141, v2
	s_and_b64 vcc, vcc, s[0:1]
	v_cmp_le_i32_e64 s[0:1], v156, v0
	v_cmp_gt_i32_e64 s[80:81], v156, v2
	s_and_b64 s[0:1], s[0:1], s[80:81]
	v_cndmask_b32_e32 v70, v236, v70, vcc
	v_cndmask_b32_e64 v54, v236, v54, s[0:1]
	v_cmp_le_i32_e32 vcc, v142, v0
	v_cmp_gt_i32_e64 s[0:1], v142, v2
	s_and_b64 vcc, vcc, s[0:1]
	v_cmp_le_i32_e64 s[0:1], v157, v0
	v_cmp_gt_i32_e64 s[80:81], v157, v2
	s_and_b64 s[0:1], s[0:1], s[80:81]
	v_cndmask_b32_e32 v71, v236, v71, vcc
	v_cndmask_b32_e64 v55, v236, v55, s[0:1]
	v_cmp_le_i32_e32 vcc, v143, v0
	v_cmp_gt_i32_e64 s[0:1], v143, v2
	s_and_b64 vcc, vcc, s[0:1]
	v_cmp_le_i32_e64 s[0:1], v158, v0
	v_cmp_gt_i32_e64 s[80:81], v158, v2
	s_and_b64 s[0:1], s[0:1], s[80:81]
	v_cndmask_b32_e32 v72, v236, v72, vcc
	v_cndmask_b32_e64 v56, v236, v56, s[0:1]
	v_cmp_le_i32_e32 vcc, v144, v0
	v_cmp_gt_i32_e64 s[0:1], v144, v2
	s_and_b64 vcc, vcc, s[0:1]
	v_cmp_le_i32_e64 s[0:1], v159, v0
	v_cmp_gt_i32_e64 s[80:81], v159, v2
	s_and_b64 s[0:1], s[0:1], s[80:81]
	v_cndmask_b32_e32 v73, v236, v73, vcc
	v_cndmask_b32_e64 v57, v236, v57, s[0:1]
	v_cmp_le_i32_e32 vcc, v145, v0
	v_cmp_gt_i32_e64 s[0:1], v145, v2
	s_and_b64 vcc, vcc, s[0:1]
	v_cmp_le_i32_e64 s[0:1], v160, v0
	v_cmp_gt_i32_e64 s[80:81], v160, v2
	s_and_b64 s[0:1], s[0:1], s[80:81]
	v_cndmask_b32_e32 v74, v236, v74, vcc
	v_cndmask_b32_e64 v58, v236, v58, s[0:1]
	v_cmp_le_i32_e32 vcc, v146, v0
	v_cmp_gt_i32_e64 s[0:1], v146, v2
	s_and_b64 vcc, vcc, s[0:1]
	v_cmp_le_i32_e64 s[0:1], v161, v0
	v_cmp_gt_i32_e64 s[80:81], v161, v2
	s_and_b64 s[0:1], s[0:1], s[80:81]
	v_cndmask_b32_e32 v75, v236, v75, vcc
	v_cndmask_b32_e64 v59, v236, v59, s[0:1]
	v_cmp_le_i32_e32 vcc, v147, v0
	v_cmp_gt_i32_e64 s[0:1], v147, v2
	s_and_b64 vcc, vcc, s[0:1]
	v_cmp_le_i32_e64 s[0:1], v162, v0
	v_cmp_gt_i32_e64 s[80:81], v162, v2
	s_and_b64 s[0:1], s[0:1], s[80:81]
	v_cndmask_b32_e32 v76, v236, v76, vcc
	v_cndmask_b32_e64 v60, v236, v60, s[0:1]
	v_cmp_le_i32_e32 vcc, v148, v0
	v_cmp_gt_i32_e64 s[0:1], v148, v2
	s_and_b64 vcc, vcc, s[0:1]
	v_cmp_le_i32_e64 s[0:1], v163, v0
	v_cmp_gt_i32_e64 s[80:81], v163, v2
	s_and_b64 s[0:1], s[0:1], s[80:81]
	v_cndmask_b32_e32 v77, v236, v77, vcc
	v_cndmask_b32_e64 v61, v236, v61, s[0:1]
	v_cmp_le_i32_e32 vcc, v149, v0
	v_cmp_gt_i32_e64 s[0:1], v149, v2
	s_and_b64 vcc, vcc, s[0:1]
	v_cmp_le_i32_e64 s[0:1], v164, v0
	v_cmp_gt_i32_e64 s[80:81], v164, v2
	s_and_b64 s[0:1], s[0:1], s[80:81]
	v_cndmask_b32_e32 v78, v236, v78, vcc
	v_cndmask_b32_e64 v62, v236, v62, s[0:1]
	v_cmp_le_i32_e32 vcc, v150, v0
	v_cmp_gt_i32_e64 s[0:1], v150, v2
	s_and_b64 vcc, vcc, s[0:1]
	v_cmp_le_i32_e64 s[0:1], v165, v0
	v_cmp_gt_i32_e64 s[80:81], v165, v2
	s_and_b64 s[0:1], s[0:1], s[80:81]
	v_cndmask_b32_e32 v79, v236, v79, vcc
	v_cndmask_b32_e64 v63, v236, v63, s[0:1]

.LBB0_1000:
	s_and_b32 s25, s26, s25
	s_and_b64 s[0:1], s[92:93], exec
	s_cselect_b32 s2, -1, s27
	s_and_b64 s[0:1], s[90:91], exec
	s_cselect_b32 s24, -1, s33
	s_cmp_lt_i32 s23, 0
	s_cselect_b64 s[0:1], -1, 0
	v_sub_f32_e32 v64, v64, v245
	v_sub_f32_e32 v48, v48, v245
	v_exp_f32_e32 v64, v64
	v_exp_f32_e32 v48, v48
	v_sub_f32_e32 v65, v65, v245
	v_sub_f32_e32 v49, v49, v245
	v_exp_f32_e32 v65, v65
	v_exp_f32_e32 v49, v49
	v_sub_f32_e32 v66, v66, v245
	v_sub_f32_e32 v50, v50, v245
	v_exp_f32_e32 v66, v66
	v_exp_f32_e32 v50, v50
	v_sub_f32_e32 v67, v67, v245
	v_sub_f32_e32 v51, v51, v245
	v_exp_f32_e32 v67, v67
	v_exp_f32_e32 v51, v51
	v_sub_f32_e32 v68, v68, v245
	v_sub_f32_e32 v52, v52, v245
	v_exp_f32_e32 v68, v68
	v_exp_f32_e32 v52, v52
	v_sub_f32_e32 v69, v69, v245
	v_sub_f32_e32 v53, v53, v245
	v_exp_f32_e32 v69, v69
	v_exp_f32_e32 v53, v53
	v_sub_f32_e32 v70, v70, v245
	v_sub_f32_e32 v54, v54, v245
	v_exp_f32_e32 v70, v70
	v_exp_f32_e32 v54, v54
	v_sub_f32_e32 v71, v71, v245
	v_sub_f32_e32 v55, v55, v245
	v_exp_f32_e32 v71, v71
	v_exp_f32_e32 v55, v55
	v_pk_add_f32 v[2:3], v[64:65], v[48:49]
	v_pk_add_f32 v[2:3], v[2:3], v[66:67]
	v_pk_add_f32 v[2:3], v[2:3], v[50:51]
	v_pk_add_f32 v[2:3], v[2:3], v[68:69]
	v_pk_add_f32 v[2:3], v[2:3], v[52:53]
	v_pk_add_f32 v[2:3], v[2:3], v[70:71]
	v_pk_add_f32 v[2:3], v[2:3], v[54:55]
	v_cvt_pk_bf16_f32 v64, v64, v65
	v_cvt_pk_bf16_f32 v65, v66, v67
	v_cvt_pk_bf16_f32 v66, v68, v69
	v_cvt_pk_bf16_f32 v67, v70, v71
	v_cvt_pk_bf16_f32 v48, v48, v49
	v_cvt_pk_bf16_f32 v49, v50, v51
	v_cvt_pk_bf16_f32 v50, v52, v53
	v_cvt_pk_bf16_f32 v51, v54, v55
	ds_read_b64_tr_b16 v[68:69], v255 offset:6208
	ds_read_b64_tr_b16 v[70:71], v255 offset:7744
	ds_read_b64_tr_b16 v[52:53], v255 offset:3072
	ds_read_b64_tr_b16 v[54:55], v255 offset:4608
	s_waitcnt lgkmcnt(8)
	v_mfma_f32_32x32x16_bf16 v[32:47], v[250:253], v[64:67], v[32:47]
	ds_read_b64_tr_b16 v[250:251], v255 offset:9216
	ds_read_b64_tr_b16 v[252:253], v255 offset:10752
	v_sub_f32_e32 v72, v72, v245
	v_sub_f32_e32 v56, v56, v245
	v_exp_f32_e32 v72, v72
	v_exp_f32_e32 v56, v56
	v_sub_f32_e32 v73, v73, v245
	v_sub_f32_e32 v57, v57, v245
	v_exp_f32_e32 v73, v73
	v_exp_f32_e32 v57, v57
	v_sub_f32_e32 v74, v74, v245
	v_sub_f32_e32 v58, v58, v245
	v_exp_f32_e32 v74, v74
	v_exp_f32_e32 v58, v58
	v_sub_f32_e32 v75, v75, v245
	v_sub_f32_e32 v59, v59, v245
	v_exp_f32_e32 v75, v75
	v_exp_f32_e32 v59, v59
	s_waitcnt lgkmcnt(8)
	v_mfma_f32_32x32x16_bf16 v[16:31], v[6:9], v[64:67], v[16:31]
	ds_read_b64_tr_b16 v[6:7], v255 offset:3136
	ds_read_b64_tr_b16 v[8:9], v255 offset:4672
	v_sub_f32_e32 v76, v76, v245
	v_sub_f32_e32 v60, v60, v245
	v_exp_f32_e32 v76, v76
	v_exp_f32_e32 v60, v60
	v_sub_f32_e32 v77, v77, v245
	v_sub_f32_e32 v61, v61, v245
	v_exp_f32_e32 v77, v77
	v_exp_f32_e32 v61, v61
	v_sub_f32_e32 v78, v78, v245
	v_sub_f32_e32 v62, v62, v245
	v_exp_f32_e32 v78, v78
	v_exp_f32_e32 v62, v62
	v_sub_f32_e32 v79, v79, v245
	v_sub_f32_e32 v63, v63, v245
	v_exp_f32_e32 v79, v79
	v_exp_f32_e32 v63, v63
	s_waitcnt lgkmcnt(8)
	v_mfma_f32_32x32x16_bf16 v[32:47], v[10:13], v[48:51], v[32:47]
	ds_read_b64_tr_b16 v[10:11], v255 offset:9280
	ds_read_b64_tr_b16 v[12:13], v255 offset:10816
	v_pk_add_f32 v[2:3], v[2:3], v[72:73]
	v_pk_add_f32 v[2:3], v[2:3], v[56:57]
	v_pk_add_f32 v[2:3], v[2:3], v[74:75]
	v_pk_add_f32 v[2:3], v[2:3], v[58:59]
	v_pk_add_f32 v[2:3], v[2:3], v[76:77]
	v_pk_add_f32 v[2:3], v[2:3], v[60:61]
	v_pk_add_f32 v[2:3], v[2:3], v[78:79]
	v_pk_add_f32 v[2:3], v[2:3], v[62:63]
	s_waitcnt lgkmcnt(8)
	v_mfma_f32_32x32x16_bf16 v[16:31], v[68:71], v[48:51], v[16:31]
	v_cvt_pk_bf16_f32 v72, v72, v73
	v_cvt_pk_bf16_f32 v73, v74, v75
	v_cvt_pk_bf16_f32 v74, v76, v77
	v_cvt_pk_bf16_f32 v75, v78, v79
	v_cvt_pk_bf16_f32 v56, v56, v57
	v_cvt_pk_bf16_f32 v57, v58, v59
	v_cvt_pk_bf16_f32 v58, v60, v61
	v_cvt_pk_bf16_f32 v59, v62, v63
	v_add_f32_e32 v2, v2, v3
	v_mov_b32_e32 v4, v2
	s_waitcnt lgkmcnt(6)
	v_mfma_f32_32x32x16_bf16 v[32:47], v[52:55], v[72:75], v[32:47]
	v_permlane32_swap_b32_e32 v4, v2
	s_waitcnt lgkmcnt(2)
	v_mfma_f32_32x32x16_bf16 v[16:31], v[6:9], v[72:75], v[16:31]
	v_add_f32_e32 v2, v2, v4
	v_add_f32_e32 v244, v244, v2
	v_mfma_f32_32x32x16_bf16 v[32:47], v[250:253], v[56:59], v[32:47]
	s_waitcnt lgkmcnt(0)
	v_mfma_f32_32x32x16_bf16 v[16:31], v[10:13], v[56:59], v[16:31]
	s_and_b64 vcc, exec, s[0:1]
	s_mov_b32 s27, s23
	s_cbranch_vccz .LBB0_985
	s_branch .LBB0_943
